# strategy 4 mirror: static s_setprio 1 for waves 0-3 instead
# speedup vs baseline: 1.0090x; 1.0013x over previous
; __global__ void __launch_bounds__(512) hybrid_megakernel(Params p) {
;     ...
;   for (int layer = 0; layer < DEPTH; ++layer) {
;     if (layer > 0) convert_weights(p, layer, lds, 2);
;     if (STOP_AFTER != 0 && STOP_AFTER == layer * 10) return;
;     phaseA(p, sl, layer, lds);
.LBB0_235:
	v_readfirstlane_b32 s0, v210
	s_nop 3
	s_lshr_b32 s0, s0, 6
	s_cmp_ge_u32 s0, 4
	s_cbranch_scc1 .Lmy_prio_done
	s_setprio 1
